# attention: next round's Q fragments prefetched with the K/V prefetch into dead VGPRs + counted vmcnt at the first score MFMA; on top of EpiRes hb store widening
# speedup vs baseline: 1.0065x; 1.0065x over previous
; #define LAS __attribute__((address_space(3)))
; DI void attn_phase(const Params& P, LAS unsigned char* lds, int b) {
;     ...
;         for (int e = 0; e < 6; ++e) {
;           const int idx = tid + e * 512, row = idx >> 3, ch = idx & 7;
;           *(LAS u32x4*)(lds + row * AT_STR + ch * 16) = pk[e];
;           *(LAS u32x4*)(lds + AT_VOFF + row * AT_STR + ch * 16) = pv[e];
;         }
;         const int wl = (NP == 2) ? (wid & 3) : wid, slab = (NP == 2) ? (wid >> 2) : 0, phase = pbase + slab;
;         const int i0 = P0 + 16 * NQ * wl, rowbase = slab * WR + 16 * NQ * wl;
;         bf16x8 qf[2][2]; unsigned long long prev[2][4]; float plse[2];
; #pragma unroll
;         for (int q = 0; q < 2; ++q) {
;           plse[q] = 0.f;
; #pragma unroll
;           for (int dt = 0; dt < 4; ++dt) prev[q][dt] = 0ull;
;           if (q < NQ) {
;             const int qtok = (i0 + 16 * q + fr) * dil + phase;
;             qf[q][0] = *(const bf16x8*)(Qg + (size_t)qtok * 64 + fq * 8);
;             qf[q][1] = *(const bf16x8*)(Qg + (size_t)qtok * 64 + 32 + fq * 8);
;             if (g > 0) {
;               plse[q] = lse[(size_t)qtok * 16 + head];
; #pragma unroll
;               for (int dt = 0; dt < 4; ++dt)
;                 prev[q][dt] = *(const unsigned long long*)(aout + (size_t)qtok * DM + head * 64 + 4 * fq + dt * 16);
;             }
;           } else { qf[q][0] = (bf16x8){0, 0, 0, 0, 0, 0, 0, 0}; qf[q][1] = qf[q][0]; }
;         }
.LBB0_312:
	v_ashrrev_i32_e32 v0, 6, v3
	s_lshl_b32 s13, s20, s67
	v_and_b32_e32 v2, 3, v0
	s_and_b64 s[0:1], s[36:37], exec
	v_cndmask_b32_e64 v0, v0, v2, s[40:41]
	s_cselect_b32 s0, s61, s66
	v_ashrrev_i32_e32 v2, 8, v3
	v_lshlrev_b32_e32 v111, s21, v0
	v_and_b32_e32 v177, 15, v3
	s_cselect_b32 s1, 0, s13
	v_cndmask_b32_e64 v110, 0, v2, s[40:41]
	v_add_u32_e32 v181, s0, v111
	v_add_u32_e32 v96, s1, v110
	v_or_b32_e32 v97, v181, v177
	v_lshl_add_u32 v98, v97, s34, v96
	v_ashrrev_i32_e32 v99, 31, v98
	v_bfe_u32 v145, v3, 4, 2
	v_lshlrev_b64 v[88:89], 7, v[98:99]
	v_lshl_add_u64 v[88:89], s[18:19], 0, v[88:89]
	v_lshlrev_b32_e32 v104, 4, v145
	v_mov_b32_e32 v105, v1
	v_lshl_add_u64 v[88:89], v[88:89], 0, v[104:105]
	v_mov_b64_e32 v[244:245], v[88:89]
	s_cmp_eq_u32 s20, 0
	s_cbranch_scc0 .Lat_q0_copy
	global_load_dwordx4 v[92:95], v[88:89], off
	s_nop 0
	global_load_dwordx4 v[88:91], v[88:89], off offset:64
	s_branch .Lat_q0_done
.Lat_q0_copy:
	s_waitcnt vmcnt(3)
	v_mov_b64_e32 v[92:93], v[228:229]
	v_mov_b64_e32 v[94:95], v[230:231]
	v_mov_b64_e32 v[88:89], v[232:233]
	v_mov_b64_e32 v[90:91], v[234:235]
.Lat_q0_done:
	v_lshlrev_b32_e32 v0, 4, v3
	v_and_b32_e32 v2, 0x70, v0
	v_add_u32_e32 v0, 0, v2
	v_ashrrev_i32_e32 v117, 3, v3
	v_mad_u64_u32 v[100:101], s[0:1], v117, s11, v[0:1]
	s_waitcnt vmcnt(3)
	ds_write_b128 v100, v[32:35]
	s_waitcnt vmcnt(2)
	ds_write_b128 v100, v[36:39] offset:59904
	v_add_u32_e32 v100, 0x200, v3
	v_ashrrev_i32_e32 v116, 3, v100
	v_mad_u64_u32 v[100:101], s[0:1], v116, s11, v[0:1]
	ds_write_b128 v100, v[40:43]
	ds_write_b128 v100, v[44:47] offset:59904
	v_add_u32_e32 v100, 0x400, v3
	v_ashrrev_i32_e32 v115, 3, v100
	v_mad_u64_u32 v[100:101], s[0:1], v115, s11, v[0:1]
	ds_write_b128 v100, v[48:51]
	ds_write_b128 v100, v[52:55] offset:59904
	v_add_u32_e32 v100, 0x600, v3
	v_ashrrev_i32_e32 v113, 3, v100
	v_mad_u64_u32 v[100:101], s[0:1], v113, s11, v[0:1]
	ds_write_b128 v100, v[60:63]
	ds_write_b128 v100, v[64:67] offset:59904
	v_add_u32_e32 v100, 0x800, v3
	v_ashrrev_i32_e32 v112, 3, v100
	v_mad_u64_u32 v[100:101], s[0:1], v112, s11, v[0:1]
	ds_write_b128 v100, v[68:71]
	ds_write_b128 v100, v[72:75] offset:59904
	v_add_u32_e32 v100, 0xa00, v3
	v_ashrrev_i32_e32 v105, 3, v100
	v_mad_u64_u32 v[100:101], s[0:1], v105, s11, v[0:1]
	ds_write_b128 v100, v[80:83]
	ds_write_b128 v100, v[84:87] offset:59904
	v_lshlrev_b32_e32 v0, 3, v145
	v_cndmask_b32_e64 v100, 0, 1, s[96:97]
	v_lshl_add_u64 v[150:151], s[90:91], 0, v[0:1]
	v_cmp_ne_u32_e64 s[42:43], 1, v100
	v_lshlrev_b64 v[100:101], 6, v[98:99]
	v_lshlrev_b64 v[98:99], 11, v[98:99]
	v_mov_b32_e32 v147, 0
	v_mov_b64_e32 v[148:149], 0
	s_andn2_b64 vcc, exec, s[96:97]
	v_lshl_add_u64 v[158:159], s[88:89], 0, v[100:101]
	v_lshl_add_u64 v[160:161], v[150:151], 0, v[98:99]
	v_mov_b64_e32 v[162:163], 0
	v_mov_b64_e32 v[164:165], 0
	v_mov_b64_e32 v[166:167], 0
	v_mov_b64_e32 v[168:169], 0
	v_mov_b32_e32 v176, 0
	s_cbranch_vccnz .LBB0_314
	global_load_dword v176, v[158:159], off
	global_load_dwordx2 v[168:169], v[160:161], off
	global_load_dwordx2 v[166:167], v[160:161], off offset:32
	global_load_dwordx2 v[164:165], v[160:161], off offset:64
	global_load_dwordx2 v[162:163], v[160:161], off offset:96
.LBB0_314:
	v_cndmask_b32_e64 v98, 0, 1, s[92:93]
	v_add_u32_e32 v97, 16, v97
	v_cmp_ne_u32_e64 s[44:45], 1, v98
	s_andn2_b64 vcc, exec, s[92:93]
	v_lshl_add_u32 v146, v97, s34, v96
	s_cbranch_vccnz .LBB0_317
	v_ashrrev_i32_e32 v147, 31, v146
	v_lshlrev_b64 v[96:97], 7, v[146:147]
	v_lshl_add_u64 v[96:97], s[18:19], 0, v[96:97]
	v_lshlrev_b32_e32 v0, 1, v0
	v_lshl_add_u64 v[96:97], v[96:97], 0, v[0:1]
	v_mov_b64_e32 v[246:247], v[96:97]
	s_cmp_eq_u32 s20, 0
	s_cbranch_scc0 .Lat_q1_copy
	global_load_dwordx4 v[100:103], v[96:97], off
	s_nop 0
	global_load_dwordx4 v[96:99], v[96:97], off offset:64
	s_branch .Lat_q1_done
.Lat_q1_copy:
	v_mov_b64_e32 v[100:101], v[236:237]
	v_mov_b64_e32 v[102:103], v[238:239]
	v_mov_b64_e32 v[96:97], v[240:241]
	v_mov_b64_e32 v[98:99], v[242:243]
.Lat_q1_done:
	s_and_b64 vcc, exec, s[42:43]
	s_cbranch_vccnz .LBB0_318
	v_lshlrev_b64 v[106:107], 6, v[146:147]
	v_lshl_add_u64 v[106:107], s[88:89], 0, v[106:107]
	v_lshlrev_b64 v[108:109], 11, v[146:147]
	v_lshl_add_u64 v[108:109], v[150:151], 0, v[108:109]
	global_load_dword v147, v[106:107], off
	global_load_dwordx2 v[156:157], v[108:109], off
	global_load_dwordx2 v[154:155], v[108:109], off offset:32
	global_load_dwordx2 v[152:153], v[108:109], off offset:64
	global_load_dwordx2 v[148:149], v[108:109], off offset:96
	s_branch .LBB0_319

; #define LBAR do { asm volatile("s_waitcnt lgkmcnt(0)" ::: "memory"); __builtin_amdgcn_s_barrier(); asm volatile("" ::: "memory"); } while (0)
; DI void attn_phase(const Params& P, LAS unsigned char* lds, int b) {
;     ...
;             const int qtok = (i0 + 16 * q + fr) * dil + phase;
;             qf[q][0] = *(const bf16x8*)(Qg + (size_t)qtok * 64 + fq * 8);
;             qf[q][1] = *(const bf16x8*)(Qg + (size_t)qtok * 64 + 32 + fq * 8);
;             if (g > 0) {
;               plse[q] = lse[(size_t)qtok * 16 + head];
; #pragma unroll
;               for (int dt = 0; dt < 4; ++dt)
;                 prev[q][dt] = *(const unsigned long long*)(aout + (size_t)qtok * DM + head * 64 + 4 * fq + dt * 16);
;             }
;           } else { qf[q][0] = (bf16x8){0, 0, 0, 0, 0, 0, 0, 0}; qf[q][1] = qf[q][0]; }
;         }
;         LBAR;
;         if (rd + 1 < nrounds) AT_LOAD(rd + 1);
.LBB0_321:
	s_andn2_b64 vcc, exec, s[0:1]
	s_mov_b32 s100, 0
	s_cbranch_vccnz .LBB0_335
	s_mov_b32 s100, 1
	s_movk_i32 s101, 0x80
	s_cmp_eq_u32 s75, 0
	s_cselect_b32 s101, 0x8000, s101
	s_cmp_eq_u32 s75, 2
	s_cselect_b32 s101, 0x100, s101
	v_add_co_u32_e32 v248, vcc, s101, v244
	s_nop 1
	v_addc_co_u32_e32 v249, vcc, 0, v245, vcc
	global_load_dwordx4 v[228:231], v[248:249], off
	global_load_dwordx4 v[232:235], v[248:249], off offset:64
	s_cmp_eq_u32 s75, 2
	s_cbranch_scc1 .Lat_noq1
	v_add_co_u32_e32 v250, vcc, s101, v246
	s_nop 1
	v_addc_co_u32_e32 v251, vcc, 0, v247, vcc
	global_load_dwordx4 v[236:239], v[250:251], off
	global_load_dwordx4 v[240:243], v[250:251], off offset:64
.Lat_noq1:
	s_add_i32 s13, s61, 0x100
	s_lshl_b32 s14, s20, s67
	s_and_b64 s[0:1], s[36:37], exec
	v_mov_b32_e32 v0, s29
	v_cmp_le_i32_e32 vcc, s29, v117
	s_cselect_b32 s0, s13, s66
	s_cselect_b32 s13, 0, s14
	v_cndmask_b32_e32 v0, 0, v0, vcc
	s_sub_i32 s14, s0, 64
	v_sub_u32_e32 v0, v117, v0
	v_add_u32_e32 v0, s14, v0
	v_mov_b32_e32 v40, v1
	v_mov_b32_e32 v41, v1
	v_mov_b32_e32 v3, v1
	v_cmp_lt_i32_e64 s[0:1], -1, v0
	v_cmp_gt_i32_e64 s[48:49], s28, v0
	v_mov_b32_e32 v42, v1
	v_mov_b32_e32 v43, v1
	v_mov_b64_e32 v[32:33], v[40:41]
	v_mov_b64_e32 v[36:37], v[40:41]
	v_lshl_add_u64 v[106:107], s[94:95], 0, v[2:3]
	v_lshl_add_u64 v[108:109], s[82:83], 0, v[2:3]
	s_and_b64 s[46:47], s[0:1], s[48:49]
	v_mov_b64_e32 v[34:35], v[42:43]
	v_mov_b64_e32 v[38:39], v[42:43]
	s_and_saveexec_b64 s[0:1], s[46:47]
	s_cselect_b32 s100, s100, 0
	s_cbranch_execz .LBB0_324
	v_cndmask_b32_e64 v2, 0, 1, vcc
	v_lshlrev_b32_e32 v0, s34, v0
	v_add3_u32 v0, s13, v2, v0
	v_lshlrev_b64 v[2:3], 7, v[0:1]
	v_lshl_add_u64 v[32:33], v[106:107], 0, v[2:3]
	v_lshl_add_u64 v[2:3], v[108:109], 0, v[2:3]
	global_load_dwordx4 v[32:35], v[32:33], off
	s_nop 0
	global_load_dwordx4 v[36:39], v[2:3], off

; #define LAS __attribute__((address_space(3)))
; DI f32x4 mfma16(bf16x8 a, bf16x8 b, f32x4 c) { return __builtin_amdgcn_mfma_f32_16x16x32_bf16(a, b, c, 0, 0, 0); }
; DI void attn_phase(const Params& P, LAS unsigned char* lds, int b) {
;     ...
;         LAS unsigned char* kb = lds + (rowbase + fr) * AT_STR + fq * 16;
;         LAS unsigned char* vb = lds + AT_VOFF + (rowbase + fq * 4 + (fr >> 2)) * AT_STR + (fr & 3) * 8;
;         f32x4 sc[2][9];
; #pragma unroll
;         for (int t = 0; t < 10; ++t) {
;           const bf16x8 k0 = *(const LAS bf16x8*)(kb + t * 16 * AT_STR), k1 = *(const LAS bf16x8*)(kb + t * 16 * AT_STR + 64);
;           if (t < 9) { f32x4 a = (f32x4){0.f, 0.f, 0.f, 0.f}; a = mfma16(k0, qf[0][0], a); a = mfma16(k1, qf[0][1], a); sc[0][t] = a; }
.LBB0_335:
	v_mad_i32_i24 v180, v110, s29, v111
	v_or_b32_e32 v0, v180, v177
	v_mul_lo_u32 v0, v0, s11
	v_add_u32_e32 v0, 0, v0
	v_add_u32_e32 v0, v0, v104
	ds_read_b128 v[104:107], v0 offset:64
	ds_read_b128 v[108:111], v0
	v_lshlrev_b32_e32 v179, 2, v145
	s_cmp_eq_u32 s100, 0
	s_cbranch_scc1 .Lat_drain
	s_cmp_eq_u32 s75, 2
	s_cbranch_scc1 .Lat_nq1w
	s_waitcnt vmcnt(16)
	s_branch .Lat_go
.Lat_nq1w:
	s_waitcnt vmcnt(14)
	s_branch .Lat_go
